# FFN1 epilogue: halo-row stores issue behind the conv-parameter wait instead of being drained by it
# speedup vs baseline: 1.0380x; 1.0070x over previous
;     __device__ __forceinline__ void operator()(AccRef acc, const Unit& u, int wr, int wc, int fr, int fq) const {
;     ...
;         float* rawu = raw + (size_t)(u.pm * 22 + u.pn) * 1024;
;         if (wr == 0 && fr == 0) {
; #pragma unroll
;             for (int bj = 0; bj < 2; ++bj)
; #pragma unroll
;                 for (int n = 0; n < 2; ++n) { *(f32x4*)(rawu + 0 * 256 + bj * 128 + clb + 4 * n) = acc[0][bj][0][n]; *(f32x4*)(rawu + 1 * 256 + bj * 128 + clb + 4 * n) = acc[0][bj][1][n]; }
;         }
;         if (wr == 1 && fr == 15) {
; #pragma unroll
;             for (int bj = 0; bj < 2; ++bj)
; #pragma unroll
;                 for (int n = 0; n < 2; ++n) { *(f32x4*)(rawu + 2 * 256 + bj * 128 + clb + 4 * n) = acc[1][bj][2][n]; *(f32x4*)(rawu + 3 * 256 + bj * 128 + clb + 4 * n) = acc[1][bj][3][n]; }
;         }
;         asm volatile("s_waitcnt lgkmcnt(0)" ::: "memory"); __builtin_amdgcn_s_barrier(); __builtin_amdgcn_s_barrier(); asm volatile("" ::: "memory");
;         const int hc0 = 128 * u.pn + clb, row0 = u.pm * 256 + wr * 64 + 4 * fr;
; #pragma unroll
;         for (int n = 0; n < 2; ++n) {
;             const f32x4 w0v = cwv[n][0], w1v = cwv[n][1], w2v = cwv[n][2], bvv = cwv[n][3], w0g = cwv[n][4], w1g = cwv[n][5], w2g = cwv[n][6], bvg = cwv[n][7];
; #pragma unroll
;             for (int ai = 0; ai < 2; ++ai) {
;                 if (n == 0 && ai == 0) {
;                     asm volatile("" ::: "memory");
;                     const float* cv = cw + hc0 + 4; const float* cg = cv + FH; const float* bp = cb + hc0 + 4;
;                     cwv[1][0] = *(const f32x4*)(cv); cwv[1][1] = *(const f32x4*)(cv + F2); cwv[1][2] = *(const f32x4*)(cv + 2 * F2); cwv[1][3] = *(const f32x4*)(bp);
;                     cwv[1][4] = *(const f32x4*)(cg); cwv[1][5] = *(const f32x4*)(cg + F2); cwv[1][6] = *(const f32x4*)(cg + 2 * F2); cwv[1][7] = *(const f32x4*)(bp + FH);
;                     asm volatile("" ::: "memory"); }
;                 f32x4 h2v = (f32x4){0.f, 0.f, 0.f, 0.f}, h3v = h2v, h2g = h2v, h3g = h2v;
;                 const int pb = ai * 2 + wr - 1;
;                 if (pb >= 0 && fr == 0) { const LAS float* xp = xch + (pb * 2) * 256 + clb + 4 * n;
;                     h2v = *(const LAS f32x4*)(xp); h3v = *(const LAS f32x4*)(xp + 256); h2g = *(const LAS f32x4*)(xp + 128); h3g = *(const LAS f32x4*)(xp + 256 + 128); }
;                 float o[4][4];
.LBB0_312:
	s_or_b64 exec, exec, s[38:39]
	s_mul_i32 s25, s34, 22
	s_add_i32 s38, s25, s35
	s_ashr_i32 s39, s38, 31
	s_lshl_b64 s[38:39], s[38:39], 12
	s_add_u32 s38, s64, s38
	s_addc_u32 s39, s65, s39
	v_lshlrev_b32_e32 v96, 2, v218
	v_or_b32_e32 v232, s36, v218
	v_ashrrev_i32_e32 v233, 31, v232
	v_lshlrev_b64 v[96:97], 2, v[232:233]
	v_lshl_add_u64 v[120:121], s[56:57], 0, v[96:97]
	v_add_co_u32_e32 v100, vcc, 0x5000, v120
	s_waitcnt lgkmcnt(0)
	s_barrier
	s_nop 0
	v_addc_co_u32_e32 v101, vcc, 0, v121, vcc
	v_add_co_u32_e32 v104, vcc, 0xb000, v120
	s_barrier
	s_nop 0
	v_addc_co_u32_e32 v105, vcc, 0, v121, vcc
	v_add_co_u32_e32 v112, vcc, s49, v120
	v_lshl_add_u64 v[124:125], s[58:59], 0, v[96:97]
	s_nop 0
	v_addc_co_u32_e32 v113, vcc, 0, v121, vcc
	v_add_co_u32_e32 v116, vcc, 0x8000, v120
	global_load_dwordx4 v[96:99], v[120:121], off offset:16
	s_nop 0
	v_addc_co_u32_e32 v117, vcc, 0, v121, vcc
	v_add_co_u32_e32 v120, vcc, 0xd000, v120
	global_load_dwordx4 v[100:103], v[100:101], off offset:2064
	s_nop 0
	global_load_dwordx4 v[104:107], v[104:105], off offset:16
	s_nop 0
	global_load_dwordx4 v[108:111], v[124:125], off offset:16
	v_addc_co_u32_e32 v121, vcc, 0, v121, vcc
	v_add_co_u32_e32 v124, vcc, 0x2000, v124
	global_load_dwordx4 v[112:115], v[112:113], off offset:3088
	s_nop 0
	global_load_dwordx4 v[116:119], v[116:117], off offset:1040
	v_addc_co_u32_e32 v125, vcc, 0, v125, vcc
	global_load_dwordx4 v[120:123], v[120:121], off offset:3088
	v_mov_b32_e32 v192, 0
	global_load_dwordx4 v[124:127], v[124:125], off offset:3088
	v_mov_b32_e32 v198, 0
	v_mov_b32_e32 v199, 0
	v_mov_b32_e32 v200, 0
	v_mov_b32_e32 v201, 0
	v_mov_b32_e32 v206, 0
	v_mov_b32_e32 v207, 0
	v_mov_b32_e32 v208, 0
	v_mov_b32_e32 v209, 0
	v_mov_b32_e32 v194, 0
	v_mov_b32_e32 v195, 0
	v_mov_b32_e32 v196, 0
	v_mov_b32_e32 v197, 0
	v_mov_b32_e32 v202, 0
	v_mov_b32_e32 v203, 0
	v_mov_b32_e32 v204, 0
	v_mov_b32_e32 v205, 0
	s_and_saveexec_b64 s[36:37], s[18:19]
	s_cbranch_execz .LBB0_318
	ds_read_b128 v[202:205], v238
	ds_read_b128 v[206:209], v238 offset:512
	ds_read_b128 v[194:197], v238 offset:1024
	ds_read_b128 v[198:201], v238 offset:1536
.LBB0_318:
	s_or_b64 exec, exec, s[36:37]
	s_waitcnt lgkmcnt(0)
	v_mov_b32_dpp v198, v140 row_shr:1 row_mask:0xf bank_mask:0xf
	v_mov_b32_dpp v199, v141 row_shr:1 row_mask:0xf bank_mask:0xf
	s_waitcnt vmcnt(8)
	v_lshlrev_b32_e32 v253, 2, v218
	s_and_saveexec_b64 s[40:41], s[10:11]
	s_cbranch_execz .LBB0_314
	global_store_dwordx4 v253, v[156:159], s[38:39]
	global_store_dwordx4 v253, v[144:147], s[38:39] offset:1024
	global_store_dwordx4 v253, v[60:63], s[38:39] offset:16
	global_store_dwordx4 v253, v[48:51], s[38:39] offset:1040
	global_store_dwordx4 v253, v[152:155], s[38:39] offset:512
	global_store_dwordx4 v253, v[132:135], s[38:39] offset:1536
	global_store_dwordx4 v253, v[56:59], s[38:39] offset:528
	global_store_dwordx4 v253, v[36:39], s[38:39] offset:1552
.LBB0_314:
	s_or_b64 exec, exec, s[40:41]
	s_and_saveexec_b64 s[40:41], s[16:17]
	s_cbranch_execz .LBB0_316
	global_store_dwordx4 v253, v[76:79], s[38:39] offset:2048
	global_store_dwordx4 v253, v[84:87], s[38:39] offset:3072
	global_store_dwordx4 v253, v[12:15], s[38:39] offset:2064
	global_store_dwordx4 v253, v[20:23], s[38:39] offset:3088
	global_store_dwordx4 v253, v[64:67], s[38:39] offset:2560
	global_store_dwordx4 v253, v[72:75], s[38:39] offset:3584
	global_store_dwordx4 v253, v[0:3], s[38:39] offset:2576
	global_store_dwordx4 v253, v[8:11], s[38:39] offset:3600
.LBB0_316:
	s_or_b64 exec, exec, s[40:41]
	v_pk_fma_f32 v[248:249], v[152:153], v[184:185], v[188:189]
	v_mov_b32_dpp v206, v128 row_shr:1 row_mask:0xf bank_mask:0xf
	v_mov_b32_dpp v207, v129 row_shr:1 row_mask:0xf bank_mask:0xf
	v_pk_fma_f32 v[248:249], v[180:181], v[198:199], v[248:249]
	v_mov_b32_dpp v194, v148 row_shr:1 row_mask:0xf bank_mask:0xf
	v_pk_fma_f32 v[206:207], v[176:177], v[206:207], v[248:249]
	v_mov_b32_dpp v195, v149 row_shr:1 row_mask:0xf bank_mask:0xf
	v_mul_f32_e32 v193, 0xbfb8aa3b, v206
	v_exp_f32_e32 v193, v193
	v_mul_f32_e32 v247, 0xbfb8aa3b, v207
	v_exp_f32_e32 v247, v247
	v_pk_fma_f32 v[250:251], v[156:157], v[168:169], v[172:173]
	v_add_f32_e32 v193, 1.0, v193
	v_rcp_f32_e32 v248, v193
	v_add_f32_e32 v193, 1.0, v247
	v_rcp_f32_e32 v249, v193
	v_mov_b32_dpp v202, v136 row_shr:1 row_mask:0xf bank_mask:0xf
	v_mov_b32_dpp v203, v137 row_shr:1 row_mask:0xf bank_mask:0xf
	v_pk_fma_f32 v[250:251], v[164:165], v[194:195], v[250:251]
	v_pk_mul_f32 v[206:207], v[206:207], v[248:249]
	v_pk_fma_f32 v[202:203], v[160:161], v[202:203], v[250:251]
	v_mov_b32_dpp v200, v142 row_shr:1 row_mask:0xf bank_mask:0xf
	v_mov_b32_dpp v201, v143 row_shr:1 row_mask:0xf bank_mask:0xf
	v_pk_mul_f32 v[202:203], v[202:203], v[206:207]
	v_pk_fma_f32 v[206:207], v[154:155], v[186:187], v[190:191]
	v_mov_b32_dpp v208, v130 row_shr:1 row_mask:0xf bank_mask:0xf
	v_mov_b32_dpp v209, v131 row_shr:1 row_mask:0xf bank_mask:0xf
	v_pk_fma_f32 v[206:207], v[182:183], v[200:201], v[206:207]
	v_mov_b32_dpp v196, v150 row_shr:1 row_mask:0xf bank_mask:0xf
	v_pk_fma_f32 v[206:207], v[178:179], v[208:209], v[206:207]
	v_mov_b32_dpp v197, v151 row_shr:1 row_mask:0xf bank_mask:0xf
	v_mul_f32_e32 v193, 0xbfb8aa3b, v206
	v_exp_f32_e32 v193, v193
	v_mul_f32_e32 v208, 0xbfb8aa3b, v207
	v_exp_f32_e32 v209, v208
	v_cvt_pk_bf16_f32 v208, v202, v203
	v_add_f32_e32 v193, 1.0, v193
	v_rcp_f32_e32 v202, v193
	v_add_f32_e32 v193, 1.0, v209
	v_rcp_f32_e32 v203, v193
	v_pk_fma_f32 v[248:249], v[158:159], v[170:171], v[174:175]
	v_mov_b32_dpp v204, v138 row_shr:1 row_mask:0xf bank_mask:0xf
	v_mov_b32_dpp v205, v139 row_shr:1 row_mask:0xf bank_mask:0xf
; #define LAS __attribute__((address_space(3)))
; __device__ __forceinline__ float sigmoidf_(float x) { return __builtin_amdgcn_rcpf(1.0f + __expf(-x)); }
;     __device__ __forceinline__ void operator()(AccRef acc, const Unit& u, int wr, int wc, int fr, int fq) const {
;     ...
;                 f32x4 h2v = (f32x4){0.f, 0.f, 0.f, 0.f}, h3v = h2v, h2g = h2v, h3g = h2v;
;                 const int pb = ai * 2 + wr - 1;
;                 if (pb >= 0 && fr == 0) { const LAS float* xp = xch + (pb * 2) * 256 + clb + 4 * n;
;                     h2v = *(const LAS f32x4*)(xp); h3v = *(const LAS f32x4*)(xp + 256); h2g = *(const LAS f32x4*)(xp + 128); h3g = *(const LAS f32x4*)(xp + 256 + 128); }
;                 float o[4][4];
; #pragma unroll
;                 for (int j = 0; j < 4; ++j) {
;                     const float v0 = acc[ai][0][0][n][j], v1 = acc[ai][0][1][n][j], v2 = acc[ai][0][2][n][j], v3 = acc[ai][0][3][n][j];
;                     const float g0 = acc[ai][1][0][n][j], g1 = acc[ai][1][1][n][j], g2 = acc[ai][1][2][n][j], g3 = acc[ai][1][3][n][j];
;                     const float pv3 = dpp_upd<0x111>(h3v[j], v3), pv2 = dpp_upd<0x111>(h2v[j], v2), pg3 = dpp_upd<0x111>(h3g[j], g3), pg2 = dpp_upd<0x111>(h2g[j], g2);
;                     const float hv0 = bvv[j] + w2v[j] * v0 + w1v[j] * pv3 + w0v[j] * pv2, hv1 = bvv[j] + w2v[j] * v1 + w1v[j] * v0 + w0v[j] * pv3;
;                     const float hv2 = bvv[j] + w2v[j] * v2 + w1v[j] * v1 + w0v[j] * v0, hv3 = bvv[j] + w2v[j] * v3 + w1v[j] * v2 + w0v[j] * v1;
;                     const float hg0 = bvg[j] + w2g[j] * g0 + w1g[j] * pg3 + w0g[j] * pg2, hg1 = bvg[j] + w2g[j] * g1 + w1g[j] * g0 + w0g[j] * pg3;
;                     const float hg2 = bvg[j] + w2g[j] * g2 + w1g[j] * g1 + w0g[j] * g0, hg3 = bvg[j] + w2g[j] * g3 + w1g[j] * g2 + w0g[j] * g1;
;                     o[0][j] = hg0 * sigmoidf_(hg0) * hv0; o[1][j] = hg1 * sigmoidf_(hg1) * hv1; o[2][j] = hg2 * sigmoidf_(hg2) * hv2; o[3][j] = hg3 * sigmoidf_(hg3) * hv3; }
; #pragma unroll
;                 for (int m = 0; m < 4; ++m) { u32x2 w; w.x = cvt_pk_bf16(o[m][0], o[m][1]); w.y = cvt_pk_bf16(o[m][2], o[m][3]);
;                     *(u32x2*)(Aout + (size_t)(row0 + ai * 128 + m) * FH + hc0 + 4 * n) = w; } } }
	v_pk_fma_f32 v[248:249], v[166:167], v[196:197], v[248:249]
	v_pk_mul_f32 v[202:203], v[206:207], v[202:203]
	v_pk_fma_f32 v[204:205], v[162:163], v[204:205], v[248:249]
	v_lshl_add_u32 v246, s34, 8, v236
	v_pk_mul_f32 v[202:203], v[204:205], v[202:203]
	v_lshlrev_b64 v[204:205], 1, v[232:233]
	v_pk_fma_f32 v[232:233], v[132:133], v[184:185], v[188:189]
	v_mov_b64_e32 v[206:207], s[60:61]
	v_pk_fma_f32 v[232:233], v[152:153], v[180:181], v[232:233]
	v_cvt_pk_bf16_f32 v209, v202, v203
	v_pk_fma_f32 v[198:199], v[176:177], v[198:199], v[232:233]
	v_mad_i64_i32 v[202:203], s[34:35], v246, s74, v[206:207]
	v_mul_f32_e32 v193, 0xbfb8aa3b, v198
	v_exp_f32_e32 v193, v193
	v_mul_f32_e32 v232, 0xbfb8aa3b, v199
	v_exp_f32_e32 v232, v232
	v_lshl_add_u64 v[202:203], v[202:203], 0, v[204:205]
	v_add_f32_e32 v193, 1.0, v193
	global_store_dwordx2 v[202:203], v[208:209], off
	v_rcp_f32_e32 v208, v193
	v_add_f32_e32 v193, 1.0, v232
	v_rcp_f32_e32 v209, v193
	v_pk_fma_f32 v[232:233], v[144:145], v[168:169], v[172:173]
	v_pk_fma_f32 v[140:141], v[140:141], v[184:185], v[188:189]
	v_pk_fma_f32 v[232:233], v[156:157], v[164:165], v[232:233]
	v_pk_mul_f32 v[198:199], v[198:199], v[208:209]
	v_pk_fma_f32 v[194:195], v[160:161], v[194:195], v[232:233]
	v_pk_fma_f32 v[208:209], v[146:147], v[170:171], v[174:175]
	v_pk_mul_f32 v[194:195], v[194:195], v[198:199]
	v_pk_fma_f32 v[198:199], v[134:135], v[186:187], v[190:191]
	v_pk_fma_f32 v[208:209], v[158:159], v[166:167], v[208:209]
	v_pk_fma_f32 v[198:199], v[154:155], v[182:183], v[198:199]
	v_pk_fma_f32 v[196:197], v[162:163], v[196:197], v[208:209]
	v_pk_fma_f32 v[198:199], v[178:179], v[200:201], v[198:199]
	v_cvt_pk_bf16_f32 v194, v194, v195
	v_mul_f32_e32 v193, 0xbfb8aa3b, v198
	v_exp_f32_e32 v193, v193
	v_mul_f32_e32 v200, 0xbfb8aa3b, v199
	v_exp_f32_e32 v201, v200
	v_pk_fma_f32 v[148:149], v[148:149], v[168:169], v[172:173]
	v_add_f32_e32 v193, 1.0, v193
	v_rcp_f32_e32 v200, v193
	v_add_f32_e32 v193, 1.0, v201
	v_rcp_f32_e32 v201, v193
	v_or_b32_e32 v193, 1, v246
	v_pk_mul_f32 v[198:199], v[198:199], v[200:201]
	s_nop 0
	v_pk_mul_f32 v[196:197], v[196:197], v[198:199]
	v_pk_fma_f32 v[198:199], v[128:129], v[184:185], v[188:189]
	v_cvt_pk_bf16_f32 v195, v196, v197
	v_pk_fma_f32 v[198:199], v[132:133], v[180:181], v[198:199]
	v_mad_i64_i32 v[196:197], s[34:35], v193, s74, v[206:207]
	v_pk_fma_f32 v[152:153], v[152:153], v[176:177], v[198:199]
	v_lshl_add_u64 v[196:197], v[196:197], 0, v[204:205]
	v_mul_f32_e32 v193, 0xbfb8aa3b, v152
	v_exp_f32_e32 v193, v193
	v_mul_f32_e32 v198, 0xbfb8aa3b, v153
	v_exp_f32_e32 v198, v198
	global_store_dwordx2 v[196:197], v[194:195], off
	v_add_f32_e32 v193, 1.0, v193
	v_rcp_f32_e32 v194, v193
	v_add_f32_e32 v193, 1.0, v198
	v_rcp_f32_e32 v195, v193
	v_pk_fma_f32 v[198:199], v[136:137], v[168:169], v[172:173]
	v_pk_fma_f32 v[128:129], v[128:129], v[180:181], v[140:141]
	v_pk_fma_f32 v[198:199], v[144:145], v[164:165], v[198:199]
	v_pk_fma_f32 v[128:129], v[132:133], v[176:177], v[128:129]
	v_pk_fma_f32 v[156:157], v[156:157], v[160:161], v[198:199]
	v_pk_mul_f32 v[152:153], v[152:153], v[194:195]
	v_mul_f32_e32 v132, 0xbfb8aa3b, v128
	v_pk_mul_f32 v[152:153], v[156:157], v[152:153]
	v_pk_fma_f32 v[156:157], v[130:131], v[186:187], v[190:191]
	v_exp_f32_e32 v140, v132
	v_pk_fma_f32 v[132:133], v[142:143], v[186:187], v[190:191]
	v_pk_fma_f32 v[156:157], v[134:135], v[182:183], v[156:157]
	v_pk_fma_f32 v[130:131], v[130:131], v[182:183], v[132:133]
	v_pk_fma_f32 v[154:155], v[154:155], v[178:179], v[156:157]
	v_pk_fma_f32 v[130:131], v[134:135], v[178:179], v[130:131]
	v_mul_f32_e32 v156, 0xbfb8aa3b, v154
	v_mul_f32_e32 v141, 0xbfb8aa3b, v129
	v_mul_f32_e32 v132, 0xbfb8aa3b, v130
	v_mul_f32_e32 v133, 0xbfb8aa3b, v131
	v_exp_f32_e32 v157, v156
	v_mul_f32_e32 v156, 0xbfb8aa3b, v155
	v_exp_f32_e32 v141, v141
	v_exp_f32_e32 v132, v132
	v_exp_f32_e32 v133, v133
	v_exp_f32_e32 v193, v156
	v_add_f32_e32 v140, 1.0, v140
	v_add_f32_e32 v141, 1.0, v141
	v_add_f32_e32 v132, 1.0, v132
	v_add_f32_e32 v133, 1.0, v133
	v_cvt_pk_bf16_f32 v156, v152, v153
	v_add_f32_e32 v152, 1.0, v157
	v_add_f32_e32 v153, 1.0, v193
	v_rcp_f32_e32 v140, v140
	v_rcp_f32_e32 v141, v141
	v_rcp_f32_e32 v132, v132
	v_rcp_f32_e32 v133, v133
	v_rcp_f32_e32 v152, v152
	v_rcp_f32_e32 v153, v153
	v_pk_fma_f32 v[142:143], v[150:151], v[170:171], v[174:175]
	v_pk_fma_f32 v[194:195], v[138:139], v[170:171], v[174:175]
	v_pk_fma_f32 v[136:137], v[136:137], v[164:165], v[148:149]
	v_pk_fma_f32 v[134:135], v[138:139], v[166:167], v[142:143]
	v_pk_fma_f32 v[194:195], v[146:147], v[166:167], v[194:195]
	v_pk_fma_f32 v[136:137], v[144:145], v[160:161], v[136:137]
	v_pk_mul_f32 v[128:129], v[128:129], v[140:141]
	v_pk_fma_f32 v[134:135], v[146:147], v[162:163], v[134:135]
	v_pk_mul_f32 v[130:131], v[130:131], v[132:133]
	v_pk_fma_f32 v[158:159], v[158:159], v[162:163], v[194:195]
	v_pk_mul_f32 v[152:153], v[154:155], v[152:153]
	v_pk_mul_f32 v[128:129], v[136:137], v[128:129]
	v_pk_mul_f32 v[130:131], v[134:135], v[130:131]
	v_pk_mul_f32 v[152:153], v[158:159], v[152:153]
	v_cvt_pk_bf16_f32 v128, v128, v129
	v_cvt_pk_bf16_f32 v129, v130, v131
	v_or_b32_e32 v130, 3, v246
	v_cvt_pk_bf16_f32 v157, v152, v153
	v_or_b32_e32 v152, 2, v246
	v_mad_i64_i32 v[130:131], s[34:35], v130, s74, v[206:207]
	v_mad_i64_i32 v[152:153], s[34:35], v152, s74, v[206:207]
	v_lshl_add_u64 v[140:141], v[130:131], 0, v[204:205]
	v_lshl_add_u64 v[152:153], v[152:153], 0, v[204:205]
	global_store_dwordx2 v[140:141], v[128:129], off
	v_mov_b32_e32 v193, 0
	v_mov_b32_e32 v194, 0
	v_mov_b32_e32 v195, 0
	v_mov_b32_e32 v136, 0
	v_mov_b32_e32 v137, 0
	v_mov_b32_e32 v138, 0
	v_mov_b32_e32 v139, 0
	v_mov_b32_e32 v128, 0
	v_mov_b32_e32 v129, 0
	v_mov_b32_e32 v130, 0
	v_mov_b32_e32 v131, 0
	v_mov_b32_e32 v132, 0
	v_mov_b32_e32 v133, 0
	v_mov_b32_e32 v134, 0
	v_mov_b32_e32 v135, 0
	global_store_dwordx2 v[152:153], v[156:157], off
	s_and_saveexec_b64 s[34:35], s[22:23]
	s_cbranch_execz .LBB0_320
	ds_read_b128 v[132:135], v237 offset:2048
	ds_read_b128 v[136:139], v237 offset:2560
	ds_read_b128 v[128:131], v237 offset:3072
	ds_read_b128 v[192:195], v237 offset:3584

;     __device__ __forceinline__ void operator()(AccRef acc, const Unit& u, int wr, int wc, int fr, int fq) const {
;     ...
;         float* rawu = raw + (size_t)(u.pm * 22 + u.pn) * 1024;
;         if (wr == 0 && fr == 0) {
; #pragma unroll
;             for (int bj = 0; bj < 2; ++bj)
; #pragma unroll
;                 for (int n = 0; n < 2; ++n) { *(f32x4*)(rawu + 0 * 256 + bj * 128 + clb + 4 * n) = acc[0][bj][0][n]; *(f32x4*)(rawu + 1 * 256 + bj * 128 + clb + 4 * n) = acc[0][bj][1][n]; }
;         }
;         if (wr == 1 && fr == 15) {
; #pragma unroll
;             for (int bj = 0; bj < 2; ++bj)
; #pragma unroll
;                 for (int n = 0; n < 2; ++n) { *(f32x4*)(rawu + 2 * 256 + bj * 128 + clb + 4 * n) = acc[1][bj][2][n]; *(f32x4*)(rawu + 3 * 256 + bj * 128 + clb + 4 * n) = acc[1][bj][3][n]; }
;         }
;         asm volatile("s_waitcnt lgkmcnt(0)" ::: "memory"); __builtin_amdgcn_s_barrier(); __builtin_amdgcn_s_barrier(); asm volatile("" ::: "memory");
;         const int hc0 = 128 * u.pn + clb, row0 = u.pm * 256 + wr * 64 + 4 * fr;
; #pragma unroll
;         for (int n = 0; n < 2; ++n) {
;             const f32x4 w0v = cwv[n][0], w1v = cwv[n][1], w2v = cwv[n][2], bvv = cwv[n][3], w0g = cwv[n][4], w1g = cwv[n][5], w2g = cwv[n][6], bvg = cwv[n][7];
; #pragma unroll
;             for (int ai = 0; ai < 2; ++ai) {
;                 if (n == 0 && ai == 0) {
;                     asm volatile("" ::: "memory");
;                     const float* cv = cw + hc0 + 4; const float* cg = cv + FH; const float* bp = cb + hc0 + 4;
;                     cwv[1][0] = *(const f32x4*)(cv); cwv[1][1] = *(const f32x4*)(cv + F2); cwv[1][2] = *(const f32x4*)(cv + 2 * F2); cwv[1][3] = *(const f32x4*)(bp);
;                     cwv[1][4] = *(const f32x4*)(cg); cwv[1][5] = *(const f32x4*)(cg + F2); cwv[1][6] = *(const f32x4*)(cg + 2 * F2); cwv[1][7] = *(const f32x4*)(bp + FH);
;                     asm volatile("" ::: "memory"); }
;                 f32x4 h2v = (f32x4){0.f, 0.f, 0.f, 0.f}, h3v = h2v, h2g = h2v, h3g = h2v;
;                 const int pb = ai * 2 + wr - 1;
;                 if (pb >= 0 && fr == 0) { const LAS float* xp = xch + (pb * 2) * 256 + clb + 4 * n;
;                     h2v = *(const LAS f32x4*)(xp); h3v = *(const LAS f32x4*)(xp + 256); h2g = *(const LAS f32x4*)(xp + 128); h3g = *(const LAS f32x4*)(xp + 256 + 128); }
;                 float o[4][4];
.LBB0_761:
	s_or_b64 exec, exec, s[44:45]
	s_mul_i32 s31, s40, 22
	s_add_i32 s44, s31, s41
	s_ashr_i32 s45, s44, 31
	s_lshl_b64 s[44:45], s[44:45], 12
	s_add_u32 s44, s64, s44
	s_addc_u32 s45, s65, s45
	v_lshlrev_b32_e32 v96, 2, v218
	v_or_b32_e32 v232, s42, v218
	v_ashrrev_i32_e32 v233, 31, v232
	v_lshlrev_b64 v[96:97], 2, v[232:233]
	v_lshl_add_u64 v[120:121], s[18:19], 0, v[96:97]
	v_add_co_u32_e32 v100, vcc, 0x5000, v120
	s_waitcnt lgkmcnt(0)
	s_barrier
	s_nop 0
	v_addc_co_u32_e32 v101, vcc, 0, v121, vcc
	v_add_co_u32_e32 v104, vcc, 0xb000, v120
	s_barrier
	s_nop 0
	v_addc_co_u32_e32 v105, vcc, 0, v121, vcc
	v_add_co_u32_e32 v112, vcc, s70, v120
	v_lshl_add_u64 v[124:125], s[22:23], 0, v[96:97]
	s_nop 0
	v_addc_co_u32_e32 v113, vcc, 0, v121, vcc
	v_add_co_u32_e32 v116, vcc, 0x8000, v120
	global_load_dwordx4 v[96:99], v[120:121], off offset:16
	s_nop 0
	v_addc_co_u32_e32 v117, vcc, 0, v121, vcc
	v_add_co_u32_e32 v120, vcc, 0xd000, v120
	global_load_dwordx4 v[100:103], v[100:101], off offset:2064
	s_nop 0
	global_load_dwordx4 v[104:107], v[104:105], off offset:16
	s_nop 0
	global_load_dwordx4 v[108:111], v[124:125], off offset:16
	v_addc_co_u32_e32 v121, vcc, 0, v121, vcc
	v_add_co_u32_e32 v124, vcc, 0x2000, v124
	global_load_dwordx4 v[112:115], v[112:113], off offset:3088
	s_nop 0
	global_load_dwordx4 v[116:119], v[116:117], off offset:1040
	v_addc_co_u32_e32 v125, vcc, 0, v125, vcc
	global_load_dwordx4 v[120:123], v[120:121], off offset:3088
	v_mov_b32_e32 v192, 0
	global_load_dwordx4 v[124:127], v[124:125], off offset:3088
	v_mov_b32_e32 v198, 0
	v_mov_b32_e32 v199, 0
	v_mov_b32_e32 v200, 0
	v_mov_b32_e32 v201, 0
	v_mov_b32_e32 v206, 0
	v_mov_b32_e32 v207, 0
	v_mov_b32_e32 v208, 0
	v_mov_b32_e32 v209, 0
	v_mov_b32_e32 v194, 0
	v_mov_b32_e32 v195, 0
	v_mov_b32_e32 v196, 0
	v_mov_b32_e32 v197, 0
	v_mov_b32_e32 v202, 0
	v_mov_b32_e32 v203, 0
	v_mov_b32_e32 v204, 0
	v_mov_b32_e32 v205, 0
	s_and_saveexec_b64 s[42:43], s[26:27]
	s_cbranch_execz .LBB0_767
	ds_read_b128 v[202:205], v238
	ds_read_b128 v[206:209], v238 offset:512
	ds_read_b128 v[194:197], v238 offset:1024
	ds_read_b128 v[198:201], v238 offset:1536
.LBB0_767:
	s_or_b64 exec, exec, s[42:43]
	s_waitcnt lgkmcnt(0)
	v_mov_b32_dpp v198, v140 row_shr:1 row_mask:0xf bank_mask:0xf
	v_mov_b32_dpp v199, v141 row_shr:1 row_mask:0xf bank_mask:0xf
	s_waitcnt vmcnt(8)
	v_lshlrev_b32_e32 v253, 2, v218
	s_and_saveexec_b64 s[46:47], s[12:13]
	s_cbranch_execz .LBB0_763
	global_store_dwordx4 v253, v[156:159], s[44:45]
	global_store_dwordx4 v253, v[144:147], s[44:45] offset:1024
	global_store_dwordx4 v253, v[60:63], s[44:45] offset:16
	global_store_dwordx4 v253, v[48:51], s[44:45] offset:1040
	global_store_dwordx4 v253, v[152:155], s[44:45] offset:512
	global_store_dwordx4 v253, v[132:135], s[44:45] offset:1536
	global_store_dwordx4 v253, v[56:59], s[44:45] offset:528
	global_store_dwordx4 v253, v[36:39], s[44:45] offset:1552
.LBB0_763:
	s_or_b64 exec, exec, s[46:47]
	s_and_saveexec_b64 s[46:47], s[24:25]
	s_cbranch_execz .LBB0_765
	global_store_dwordx4 v253, v[76:79], s[44:45] offset:2048
	global_store_dwordx4 v253, v[84:87], s[44:45] offset:3072
	global_store_dwordx4 v253, v[12:15], s[44:45] offset:2064
	global_store_dwordx4 v253, v[20:23], s[44:45] offset:3088
	global_store_dwordx4 v253, v[64:67], s[44:45] offset:2560
	global_store_dwordx4 v253, v[72:75], s[44:45] offset:3584
	global_store_dwordx4 v253, v[0:3], s[44:45] offset:2576
	global_store_dwordx4 v253, v[8:11], s[44:45] offset:3600
.LBB0_765:
	s_or_b64 exec, exec, s[46:47]
	v_pk_fma_f32 v[248:249], v[152:153], v[184:185], v[188:189]
	v_mov_b32_dpp v206, v128 row_shr:1 row_mask:0xf bank_mask:0xf
	v_mov_b32_dpp v207, v129 row_shr:1 row_mask:0xf bank_mask:0xf
	v_pk_fma_f32 v[248:249], v[180:181], v[198:199], v[248:249]
	v_mov_b32_dpp v194, v148 row_shr:1 row_mask:0xf bank_mask:0xf
	v_pk_fma_f32 v[206:207], v[176:177], v[206:207], v[248:249]
	v_mov_b32_dpp v195, v149 row_shr:1 row_mask:0xf bank_mask:0xf
	v_mul_f32_e32 v193, 0xbfb8aa3b, v206
	v_exp_f32_e32 v193, v193
	v_mul_f32_e32 v247, 0xbfb8aa3b, v207
	v_exp_f32_e32 v247, v247
	v_pk_fma_f32 v[250:251], v[156:157], v[168:169], v[172:173]
	v_add_f32_e32 v193, 1.0, v193
	v_rcp_f32_e32 v248, v193
	v_add_f32_e32 v193, 1.0, v247
	v_rcp_f32_e32 v249, v193
	v_mov_b32_dpp v202, v136 row_shr:1 row_mask:0xf bank_mask:0xf
	v_mov_b32_dpp v203, v137 row_shr:1 row_mask:0xf bank_mask:0xf
	v_pk_fma_f32 v[250:251], v[164:165], v[194:195], v[250:251]
	v_pk_mul_f32 v[206:207], v[206:207], v[248:249]
	v_pk_fma_f32 v[202:203], v[160:161], v[202:203], v[250:251]
	v_mov_b32_dpp v200, v142 row_shr:1 row_mask:0xf bank_mask:0xf
	v_mov_b32_dpp v201, v143 row_shr:1 row_mask:0xf bank_mask:0xf
	v_pk_mul_f32 v[202:203], v[202:203], v[206:207]
	v_pk_fma_f32 v[206:207], v[154:155], v[186:187], v[190:191]
	v_mov_b32_dpp v208, v130 row_shr:1 row_mask:0xf bank_mask:0xf
	v_mov_b32_dpp v209, v131 row_shr:1 row_mask:0xf bank_mask:0xf
	v_pk_fma_f32 v[206:207], v[182:183], v[200:201], v[206:207]
	v_mov_b32_dpp v196, v150 row_shr:1 row_mask:0xf bank_mask:0xf
	v_pk_fma_f32 v[206:207], v[178:179], v[208:209], v[206:207]
	v_mov_b32_dpp v197, v151 row_shr:1 row_mask:0xf bank_mask:0xf
	v_mul_f32_e32 v193, 0xbfb8aa3b, v206
	v_exp_f32_e32 v193, v193
	v_mul_f32_e32 v208, 0xbfb8aa3b, v207
	v_exp_f32_e32 v209, v208
	v_cvt_pk_bf16_f32 v208, v202, v203
	v_add_f32_e32 v193, 1.0, v193
	v_rcp_f32_e32 v202, v193
	v_add_f32_e32 v193, 1.0, v209
	v_rcp_f32_e32 v203, v193
	v_pk_fma_f32 v[248:249], v[158:159], v[170:171], v[174:175]
	v_mov_b32_dpp v204, v138 row_shr:1 row_mask:0xf bank_mask:0xf
	v_mov_b32_dpp v205, v139 row_shr:1 row_mask:0xf bank_mask:0xf
; #define LAS __attribute__((address_space(3)))
; __device__ __forceinline__ float sigmoidf_(float x) { return __builtin_amdgcn_rcpf(1.0f + __expf(-x)); }
;     __device__ __forceinline__ void operator()(AccRef acc, const Unit& u, int wr, int wc, int fr, int fq) const {
;     ...
;                 f32x4 h2v = (f32x4){0.f, 0.f, 0.f, 0.f}, h3v = h2v, h2g = h2v, h3g = h2v;
;                 const int pb = ai * 2 + wr - 1;
;                 if (pb >= 0 && fr == 0) { const LAS float* xp = xch + (pb * 2) * 256 + clb + 4 * n;
;                     h2v = *(const LAS f32x4*)(xp); h3v = *(const LAS f32x4*)(xp + 256); h2g = *(const LAS f32x4*)(xp + 128); h3g = *(const LAS f32x4*)(xp + 256 + 128); }
;                 float o[4][4];
; #pragma unroll
;                 for (int j = 0; j < 4; ++j) {
;                     const float v0 = acc[ai][0][0][n][j], v1 = acc[ai][0][1][n][j], v2 = acc[ai][0][2][n][j], v3 = acc[ai][0][3][n][j];
;                     const float g0 = acc[ai][1][0][n][j], g1 = acc[ai][1][1][n][j], g2 = acc[ai][1][2][n][j], g3 = acc[ai][1][3][n][j];
;                     const float pv3 = dpp_upd<0x111>(h3v[j], v3), pv2 = dpp_upd<0x111>(h2v[j], v2), pg3 = dpp_upd<0x111>(h3g[j], g3), pg2 = dpp_upd<0x111>(h2g[j], g2);
;                     const float hv0 = bvv[j] + w2v[j] * v0 + w1v[j] * pv3 + w0v[j] * pv2, hv1 = bvv[j] + w2v[j] * v1 + w1v[j] * v0 + w0v[j] * pv3;
;                     const float hv2 = bvv[j] + w2v[j] * v2 + w1v[j] * v1 + w0v[j] * v0, hv3 = bvv[j] + w2v[j] * v3 + w1v[j] * v2 + w0v[j] * v1;
;                     const float hg0 = bvg[j] + w2g[j] * g0 + w1g[j] * pg3 + w0g[j] * pg2, hg1 = bvg[j] + w2g[j] * g1 + w1g[j] * g0 + w0g[j] * pg3;
;                     const float hg2 = bvg[j] + w2g[j] * g2 + w1g[j] * g1 + w0g[j] * g0, hg3 = bvg[j] + w2g[j] * g3 + w1g[j] * g2 + w0g[j] * g1;
;                     o[0][j] = hg0 * sigmoidf_(hg0) * hv0; o[1][j] = hg1 * sigmoidf_(hg1) * hv1; o[2][j] = hg2 * sigmoidf_(hg2) * hv2; o[3][j] = hg3 * sigmoidf_(hg3) * hv3; }
; #pragma unroll
;                 for (int m = 0; m < 4; ++m) { u32x2 w; w.x = cvt_pk_bf16(o[m][0], o[m][1]); w.y = cvt_pk_bf16(o[m][2], o[m][3]);
;                     *(u32x2*)(Aout + (size_t)(row0 + ai * 128 + m) * FH + hc0 + 4 * n) = w; } } }
	v_pk_fma_f32 v[248:249], v[166:167], v[196:197], v[248:249]
	v_pk_mul_f32 v[202:203], v[206:207], v[202:203]
	v_pk_fma_f32 v[204:205], v[162:163], v[204:205], v[248:249]
	v_lshl_add_u32 v246, s40, 8, v236
	v_pk_mul_f32 v[202:203], v[204:205], v[202:203]
	v_lshlrev_b64 v[204:205], 1, v[232:233]
	v_pk_fma_f32 v[232:233], v[132:133], v[184:185], v[188:189]
	v_mov_b64_e32 v[206:207], s[60:61]
	v_pk_fma_f32 v[232:233], v[152:153], v[180:181], v[232:233]
	v_cvt_pk_bf16_f32 v209, v202, v203
	v_pk_fma_f32 v[198:199], v[176:177], v[198:199], v[232:233]
	v_mad_i64_i32 v[202:203], s[40:41], v246, s76, v[206:207]
	v_mul_f32_e32 v193, 0xbfb8aa3b, v198
	v_exp_f32_e32 v193, v193
	v_mul_f32_e32 v232, 0xbfb8aa3b, v199
	v_exp_f32_e32 v232, v232
	v_lshl_add_u64 v[202:203], v[202:203], 0, v[204:205]
	v_add_f32_e32 v193, 1.0, v193
	global_store_dwordx2 v[202:203], v[208:209], off
	v_rcp_f32_e32 v208, v193
	v_add_f32_e32 v193, 1.0, v232
	v_rcp_f32_e32 v209, v193
	v_pk_fma_f32 v[232:233], v[144:145], v[168:169], v[172:173]
	v_pk_fma_f32 v[140:141], v[140:141], v[184:185], v[188:189]
	v_pk_fma_f32 v[232:233], v[156:157], v[164:165], v[232:233]
	v_pk_mul_f32 v[198:199], v[198:199], v[208:209]
	v_pk_fma_f32 v[194:195], v[160:161], v[194:195], v[232:233]
	v_pk_fma_f32 v[208:209], v[146:147], v[170:171], v[174:175]
	v_pk_mul_f32 v[194:195], v[194:195], v[198:199]
	v_pk_fma_f32 v[198:199], v[134:135], v[186:187], v[190:191]
	v_pk_fma_f32 v[208:209], v[158:159], v[166:167], v[208:209]
	v_pk_fma_f32 v[198:199], v[154:155], v[182:183], v[198:199]
	v_pk_fma_f32 v[196:197], v[162:163], v[196:197], v[208:209]
	v_pk_fma_f32 v[198:199], v[178:179], v[200:201], v[198:199]
	v_cvt_pk_bf16_f32 v194, v194, v195
	v_mul_f32_e32 v193, 0xbfb8aa3b, v198
	v_exp_f32_e32 v193, v193
	v_mul_f32_e32 v200, 0xbfb8aa3b, v199
	v_exp_f32_e32 v201, v200
	v_pk_fma_f32 v[148:149], v[148:149], v[168:169], v[172:173]
	v_add_f32_e32 v193, 1.0, v193
	v_rcp_f32_e32 v200, v193
	v_add_f32_e32 v193, 1.0, v201
	v_rcp_f32_e32 v201, v193
	v_or_b32_e32 v193, 1, v246
	v_pk_mul_f32 v[198:199], v[198:199], v[200:201]
	s_nop 0
	v_pk_mul_f32 v[196:197], v[196:197], v[198:199]
	v_pk_fma_f32 v[198:199], v[128:129], v[184:185], v[188:189]
	v_cvt_pk_bf16_f32 v195, v196, v197
	v_pk_fma_f32 v[198:199], v[132:133], v[180:181], v[198:199]
	v_mad_i64_i32 v[196:197], s[40:41], v193, s76, v[206:207]
	v_pk_fma_f32 v[152:153], v[152:153], v[176:177], v[198:199]
	v_lshl_add_u64 v[196:197], v[196:197], 0, v[204:205]
	v_mul_f32_e32 v193, 0xbfb8aa3b, v152
	v_exp_f32_e32 v193, v193
	v_mul_f32_e32 v198, 0xbfb8aa3b, v153
	v_exp_f32_e32 v198, v198
	global_store_dwordx2 v[196:197], v[194:195], off
	v_add_f32_e32 v193, 1.0, v193
	v_rcp_f32_e32 v194, v193
	v_add_f32_e32 v193, 1.0, v198
	v_rcp_f32_e32 v195, v193
	v_pk_fma_f32 v[198:199], v[136:137], v[168:169], v[172:173]
	v_pk_fma_f32 v[128:129], v[128:129], v[180:181], v[140:141]
	v_pk_fma_f32 v[198:199], v[144:145], v[164:165], v[198:199]
	v_pk_fma_f32 v[128:129], v[132:133], v[176:177], v[128:129]
	v_pk_fma_f32 v[156:157], v[156:157], v[160:161], v[198:199]
	v_pk_mul_f32 v[152:153], v[152:153], v[194:195]
	v_mul_f32_e32 v132, 0xbfb8aa3b, v128
	v_pk_mul_f32 v[152:153], v[156:157], v[152:153]
	v_pk_fma_f32 v[156:157], v[130:131], v[186:187], v[190:191]
	v_exp_f32_e32 v140, v132
	v_pk_fma_f32 v[132:133], v[142:143], v[186:187], v[190:191]
	v_pk_fma_f32 v[156:157], v[134:135], v[182:183], v[156:157]
	v_pk_fma_f32 v[130:131], v[130:131], v[182:183], v[132:133]
	v_pk_fma_f32 v[154:155], v[154:155], v[178:179], v[156:157]
	v_pk_fma_f32 v[130:131], v[134:135], v[178:179], v[130:131]
	v_mul_f32_e32 v156, 0xbfb8aa3b, v154
	v_mul_f32_e32 v141, 0xbfb8aa3b, v129
	v_mul_f32_e32 v132, 0xbfb8aa3b, v130
	v_mul_f32_e32 v133, 0xbfb8aa3b, v131
	v_exp_f32_e32 v157, v156
	v_mul_f32_e32 v156, 0xbfb8aa3b, v155
	v_exp_f32_e32 v141, v141
	v_exp_f32_e32 v132, v132
	v_exp_f32_e32 v133, v133
	v_exp_f32_e32 v193, v156
	v_add_f32_e32 v140, 1.0, v140
	v_add_f32_e32 v141, 1.0, v141
	v_add_f32_e32 v132, 1.0, v132
	v_add_f32_e32 v133, 1.0, v133
	v_cvt_pk_bf16_f32 v156, v152, v153
	v_add_f32_e32 v152, 1.0, v157
	v_add_f32_e32 v153, 1.0, v193
	v_rcp_f32_e32 v140, v140
	v_rcp_f32_e32 v141, v141
	v_rcp_f32_e32 v132, v132
	v_rcp_f32_e32 v133, v133
	v_rcp_f32_e32 v152, v152
	v_rcp_f32_e32 v153, v153
	v_pk_fma_f32 v[142:143], v[150:151], v[170:171], v[174:175]
	v_pk_fma_f32 v[194:195], v[138:139], v[170:171], v[174:175]
	v_pk_fma_f32 v[136:137], v[136:137], v[164:165], v[148:149]
	v_pk_fma_f32 v[134:135], v[138:139], v[166:167], v[142:143]
	v_pk_fma_f32 v[194:195], v[146:147], v[166:167], v[194:195]
	v_pk_fma_f32 v[136:137], v[144:145], v[160:161], v[136:137]
	v_pk_mul_f32 v[128:129], v[128:129], v[140:141]
	v_pk_fma_f32 v[134:135], v[146:147], v[162:163], v[134:135]
	v_pk_mul_f32 v[130:131], v[130:131], v[132:133]
	v_pk_fma_f32 v[158:159], v[158:159], v[162:163], v[194:195]
	v_pk_mul_f32 v[152:153], v[154:155], v[152:153]
	v_pk_mul_f32 v[128:129], v[136:137], v[128:129]
	v_pk_mul_f32 v[130:131], v[134:135], v[130:131]
	v_pk_mul_f32 v[152:153], v[158:159], v[152:153]
	v_cvt_pk_bf16_f32 v128, v128, v129
	v_cvt_pk_bf16_f32 v129, v130, v131
	v_or_b32_e32 v130, 3, v246
	v_cvt_pk_bf16_f32 v157, v152, v153
	v_or_b32_e32 v152, 2, v246
	v_mad_i64_i32 v[130:131], s[40:41], v130, s76, v[206:207]
	v_mad_i64_i32 v[152:153], s[40:41], v152, s76, v[206:207]
	v_lshl_add_u64 v[140:141], v[130:131], 0, v[204:205]
	v_lshl_add_u64 v[152:153], v[152:153], 0, v[204:205]
	global_store_dwordx2 v[140:141], v[128:129], off
	v_mov_b32_e32 v193, 0
	v_mov_b32_e32 v194, 0
	v_mov_b32_e32 v195, 0
	v_mov_b32_e32 v136, 0
	v_mov_b32_e32 v137, 0
	v_mov_b32_e32 v138, 0
	v_mov_b32_e32 v139, 0
	v_mov_b32_e32 v128, 0
	v_mov_b32_e32 v129, 0
	v_mov_b32_e32 v130, 0
	v_mov_b32_e32 v131, 0
	v_mov_b32_e32 v132, 0
	v_mov_b32_e32 v133, 0
	v_mov_b32_e32 v134, 0
	v_mov_b32_e32 v135, 0
	global_store_dwordx2 v[152:153], v[156:157], off
	s_and_saveexec_b64 s[40:41], s[28:29]
	s_cbranch_execz .LBB0_769
	ds_read_b128 v[132:135], v237 offset:2048
	ds_read_b128 v[136:139], v237 offset:2560
	ds_read_b128 v[128:131], v237 offset:3072
	ds_read_b128 v[192:195], v237 offset:3584

;     __device__ __forceinline__ void operator()(AccRef acc, const Unit& u, int wr, int wc, int fr, int fq) const {
;     ...
;         float* rawu = raw + (size_t)(u.pm * 22 + u.pn) * 1024;
;         if (wr == 0 && fr == 0) {
; #pragma unroll
;             for (int bj = 0; bj < 2; ++bj)
; #pragma unroll
;                 for (int n = 0; n < 2; ++n) { *(f32x4*)(rawu + 0 * 256 + bj * 128 + clb + 4 * n) = acc[0][bj][0][n]; *(f32x4*)(rawu + 1 * 256 + bj * 128 + clb + 4 * n) = acc[0][bj][1][n]; }
;         }
;         if (wr == 1 && fr == 15) {
; #pragma unroll
;             for (int bj = 0; bj < 2; ++bj)
; #pragma unroll
;                 for (int n = 0; n < 2; ++n) { *(f32x4*)(rawu + 2 * 256 + bj * 128 + clb + 4 * n) = acc[1][bj][2][n]; *(f32x4*)(rawu + 3 * 256 + bj * 128 + clb + 4 * n) = acc[1][bj][3][n]; }
;         }
;         asm volatile("s_waitcnt lgkmcnt(0)" ::: "memory"); __builtin_amdgcn_s_barrier(); __builtin_amdgcn_s_barrier(); asm volatile("" ::: "memory");
;         const int hc0 = 128 * u.pn + clb, row0 = u.pm * 256 + wr * 64 + 4 * fr;
; #pragma unroll
;         for (int n = 0; n < 2; ++n) {
;             const f32x4 w0v = cwv[n][0], w1v = cwv[n][1], w2v = cwv[n][2], bvv = cwv[n][3], w0g = cwv[n][4], w1g = cwv[n][5], w2g = cwv[n][6], bvg = cwv[n][7];
; #pragma unroll
;             for (int ai = 0; ai < 2; ++ai) {
;                 if (n == 0 && ai == 0) {
;                     asm volatile("" ::: "memory");
;                     const float* cv = cw + hc0 + 4; const float* cg = cv + FH; const float* bp = cb + hc0 + 4;
;                     cwv[1][0] = *(const f32x4*)(cv); cwv[1][1] = *(const f32x4*)(cv + F2); cwv[1][2] = *(const f32x4*)(cv + 2 * F2); cwv[1][3] = *(const f32x4*)(bp);
;                     cwv[1][4] = *(const f32x4*)(cg); cwv[1][5] = *(const f32x4*)(cg + F2); cwv[1][6] = *(const f32x4*)(cg + 2 * F2); cwv[1][7] = *(const f32x4*)(bp + FH);
;                     asm volatile("" ::: "memory"); }
;                 f32x4 h2v = (f32x4){0.f, 0.f, 0.f, 0.f}, h3v = h2v, h2g = h2v, h3g = h2v;
;                 const int pb = ai * 2 + wr - 1;
;                 if (pb >= 0 && fr == 0) { const LAS float* xp = xch + (pb * 2) * 256 + clb + 4 * n;
;                     h2v = *(const LAS f32x4*)(xp); h3v = *(const LAS f32x4*)(xp + 256); h2g = *(const LAS f32x4*)(xp + 128); h3g = *(const LAS f32x4*)(xp + 256 + 128); }
;                 float o[4][4];
.LBB0_1362:
	s_or_b64 exec, exec, s[46:47]
	s_mul_i32 s35, s42, 22
	s_add_i32 s46, s35, s43
	s_ashr_i32 s47, s46, 31
	s_lshl_b64 s[46:47], s[46:47], 12
	s_add_u32 s46, s64, s46
	s_addc_u32 s47, s65, s47
	v_lshlrev_b32_e32 v96, 2, v218
	v_or_b32_e32 v232, s44, v218
	v_ashrrev_i32_e32 v233, 31, v232
	v_lshlrev_b64 v[96:97], 2, v[232:233]
	v_lshl_add_u64 v[120:121], s[16:17], 0, v[96:97]
	v_add_co_u32_e32 v100, vcc, 0x5000, v120
	s_waitcnt lgkmcnt(0)
	s_barrier
	s_nop 0
	v_addc_co_u32_e32 v101, vcc, 0, v121, vcc
	v_add_co_u32_e32 v104, vcc, 0xb000, v120
	s_barrier
	s_nop 0
	v_addc_co_u32_e32 v105, vcc, 0, v121, vcc
	v_add_co_u32_e32 v112, vcc, s76, v120
	v_lshl_add_u64 v[124:125], s[22:23], 0, v[96:97]
	s_nop 0
	v_addc_co_u32_e32 v113, vcc, 0, v121, vcc
	v_add_co_u32_e32 v116, vcc, 0x8000, v120
	global_load_dwordx4 v[96:99], v[120:121], off offset:16
	s_nop 0
	v_addc_co_u32_e32 v117, vcc, 0, v121, vcc
	v_add_co_u32_e32 v120, vcc, 0xd000, v120
	global_load_dwordx4 v[100:103], v[100:101], off offset:2064
	s_nop 0
	global_load_dwordx4 v[104:107], v[104:105], off offset:16
	s_nop 0
	global_load_dwordx4 v[108:111], v[124:125], off offset:16
	v_addc_co_u32_e32 v121, vcc, 0, v121, vcc
	v_add_co_u32_e32 v124, vcc, 0x2000, v124
	global_load_dwordx4 v[112:115], v[112:113], off offset:3088
	s_nop 0
	global_load_dwordx4 v[116:119], v[116:117], off offset:1040
	v_addc_co_u32_e32 v125, vcc, 0, v125, vcc
	global_load_dwordx4 v[120:123], v[120:121], off offset:3088
	v_mov_b32_e32 v192, 0
	global_load_dwordx4 v[124:127], v[124:125], off offset:3088
	v_mov_b32_e32 v198, 0
	v_mov_b32_e32 v199, 0
	v_mov_b32_e32 v200, 0
	v_mov_b32_e32 v201, 0
	v_mov_b32_e32 v206, 0
	v_mov_b32_e32 v207, 0
	v_mov_b32_e32 v208, 0
	v_mov_b32_e32 v209, 0
	v_mov_b32_e32 v194, 0
	v_mov_b32_e32 v195, 0
	v_mov_b32_e32 v196, 0
	v_mov_b32_e32 v197, 0
	v_mov_b32_e32 v202, 0
	v_mov_b32_e32 v203, 0
	v_mov_b32_e32 v204, 0
	v_mov_b32_e32 v205, 0
	s_and_saveexec_b64 s[44:45], s[28:29]
	s_cbranch_execz .LBB0_1368
	ds_read_b128 v[202:205], v238
	ds_read_b128 v[206:209], v238 offset:512
	ds_read_b128 v[194:197], v238 offset:1024
	ds_read_b128 v[198:201], v238 offset:1536
.LBB0_1368:
	s_or_b64 exec, exec, s[44:45]
	s_waitcnt lgkmcnt(0)
	v_mov_b32_dpp v198, v140 row_shr:1 row_mask:0xf bank_mask:0xf
	v_mov_b32_dpp v199, v141 row_shr:1 row_mask:0xf bank_mask:0xf
	s_waitcnt vmcnt(8)
	v_lshlrev_b32_e32 v253, 2, v218
	s_and_saveexec_b64 s[48:49], s[12:13]
	s_cbranch_execz .LBB0_1364
	global_store_dwordx4 v253, v[156:159], s[46:47]
	global_store_dwordx4 v253, v[144:147], s[46:47] offset:1024
	global_store_dwordx4 v253, v[60:63], s[46:47] offset:16
	global_store_dwordx4 v253, v[48:51], s[46:47] offset:1040
	global_store_dwordx4 v253, v[152:155], s[46:47] offset:512
	global_store_dwordx4 v253, v[132:135], s[46:47] offset:1536
	global_store_dwordx4 v253, v[56:59], s[46:47] offset:528
	global_store_dwordx4 v253, v[36:39], s[46:47] offset:1552
.LBB0_1364:
	s_or_b64 exec, exec, s[48:49]
	s_and_saveexec_b64 s[48:49], s[26:27]
	s_cbranch_execz .LBB0_1366
	global_store_dwordx4 v253, v[76:79], s[46:47] offset:2048
	global_store_dwordx4 v253, v[84:87], s[46:47] offset:3072
	global_store_dwordx4 v253, v[12:15], s[46:47] offset:2064
	global_store_dwordx4 v253, v[20:23], s[46:47] offset:3088
	global_store_dwordx4 v253, v[64:67], s[46:47] offset:2560
	global_store_dwordx4 v253, v[72:75], s[46:47] offset:3584
	global_store_dwordx4 v253, v[0:3], s[46:47] offset:2576
	global_store_dwordx4 v253, v[8:11], s[46:47] offset:3600
.LBB0_1366:
	s_or_b64 exec, exec, s[48:49]
	v_pk_fma_f32 v[248:249], v[152:153], v[184:185], v[188:189]
	v_mov_b32_dpp v206, v128 row_shr:1 row_mask:0xf bank_mask:0xf
	v_mov_b32_dpp v207, v129 row_shr:1 row_mask:0xf bank_mask:0xf
	v_pk_fma_f32 v[248:249], v[180:181], v[198:199], v[248:249]
	v_mov_b32_dpp v194, v148 row_shr:1 row_mask:0xf bank_mask:0xf
	v_pk_fma_f32 v[206:207], v[176:177], v[206:207], v[248:249]
	v_mov_b32_dpp v195, v149 row_shr:1 row_mask:0xf bank_mask:0xf
	v_mul_f32_e32 v193, 0xbfb8aa3b, v206
	v_exp_f32_e32 v193, v193
	v_mul_f32_e32 v247, 0xbfb8aa3b, v207
	v_exp_f32_e32 v247, v247
	v_pk_fma_f32 v[250:251], v[156:157], v[168:169], v[172:173]
	v_add_f32_e32 v193, 1.0, v193
	v_rcp_f32_e32 v248, v193
	v_add_f32_e32 v193, 1.0, v247
	v_rcp_f32_e32 v249, v193
	v_mov_b32_dpp v202, v136 row_shr:1 row_mask:0xf bank_mask:0xf
	v_mov_b32_dpp v203, v137 row_shr:1 row_mask:0xf bank_mask:0xf
	v_pk_fma_f32 v[250:251], v[164:165], v[194:195], v[250:251]
	v_pk_mul_f32 v[206:207], v[206:207], v[248:249]
	v_pk_fma_f32 v[202:203], v[160:161], v[202:203], v[250:251]
	v_mov_b32_dpp v200, v142 row_shr:1 row_mask:0xf bank_mask:0xf
	v_mov_b32_dpp v201, v143 row_shr:1 row_mask:0xf bank_mask:0xf
	v_pk_mul_f32 v[202:203], v[202:203], v[206:207]
	v_pk_fma_f32 v[206:207], v[154:155], v[186:187], v[190:191]
	v_mov_b32_dpp v208, v130 row_shr:1 row_mask:0xf bank_mask:0xf
	v_mov_b32_dpp v209, v131 row_shr:1 row_mask:0xf bank_mask:0xf
	v_pk_fma_f32 v[206:207], v[182:183], v[200:201], v[206:207]
	v_mov_b32_dpp v196, v150 row_shr:1 row_mask:0xf bank_mask:0xf
	v_pk_fma_f32 v[206:207], v[178:179], v[208:209], v[206:207]
	v_mov_b32_dpp v197, v151 row_shr:1 row_mask:0xf bank_mask:0xf
	v_mul_f32_e32 v193, 0xbfb8aa3b, v206
	v_exp_f32_e32 v193, v193
	v_mul_f32_e32 v208, 0xbfb8aa3b, v207
	v_exp_f32_e32 v209, v208
	v_cvt_pk_bf16_f32 v208, v202, v203
	v_add_f32_e32 v193, 1.0, v193
	v_rcp_f32_e32 v202, v193
	v_add_f32_e32 v193, 1.0, v209
	v_rcp_f32_e32 v203, v193
	v_pk_fma_f32 v[248:249], v[158:159], v[170:171], v[174:175]
	v_mov_b32_dpp v204, v138 row_shr:1 row_mask:0xf bank_mask:0xf
	v_mov_b32_dpp v205, v139 row_shr:1 row_mask:0xf bank_mask:0xf
; #define LAS __attribute__((address_space(3)))
; __device__ __forceinline__ float sigmoidf_(float x) { return __builtin_amdgcn_rcpf(1.0f + __expf(-x)); }
;     __device__ __forceinline__ void operator()(AccRef acc, const Unit& u, int wr, int wc, int fr, int fq) const {
;     ...
;                 f32x4 h2v = (f32x4){0.f, 0.f, 0.f, 0.f}, h3v = h2v, h2g = h2v, h3g = h2v;
;                 const int pb = ai * 2 + wr - 1;
;                 if (pb >= 0 && fr == 0) { const LAS float* xp = xch + (pb * 2) * 256 + clb + 4 * n;
;                     h2v = *(const LAS f32x4*)(xp); h3v = *(const LAS f32x4*)(xp + 256); h2g = *(const LAS f32x4*)(xp + 128); h3g = *(const LAS f32x4*)(xp + 256 + 128); }
;                 float o[4][4];
; #pragma unroll
;                 for (int j = 0; j < 4; ++j) {
;                     const float v0 = acc[ai][0][0][n][j], v1 = acc[ai][0][1][n][j], v2 = acc[ai][0][2][n][j], v3 = acc[ai][0][3][n][j];
;                     const float g0 = acc[ai][1][0][n][j], g1 = acc[ai][1][1][n][j], g2 = acc[ai][1][2][n][j], g3 = acc[ai][1][3][n][j];
;                     const float pv3 = dpp_upd<0x111>(h3v[j], v3), pv2 = dpp_upd<0x111>(h2v[j], v2), pg3 = dpp_upd<0x111>(h3g[j], g3), pg2 = dpp_upd<0x111>(h2g[j], g2);
;                     const float hv0 = bvv[j] + w2v[j] * v0 + w1v[j] * pv3 + w0v[j] * pv2, hv1 = bvv[j] + w2v[j] * v1 + w1v[j] * v0 + w0v[j] * pv3;
;                     const float hv2 = bvv[j] + w2v[j] * v2 + w1v[j] * v1 + w0v[j] * v0, hv3 = bvv[j] + w2v[j] * v3 + w1v[j] * v2 + w0v[j] * v1;
;                     const float hg0 = bvg[j] + w2g[j] * g0 + w1g[j] * pg3 + w0g[j] * pg2, hg1 = bvg[j] + w2g[j] * g1 + w1g[j] * g0 + w0g[j] * pg3;
;                     const float hg2 = bvg[j] + w2g[j] * g2 + w1g[j] * g1 + w0g[j] * g0, hg3 = bvg[j] + w2g[j] * g3 + w1g[j] * g2 + w0g[j] * g1;
;                     o[0][j] = hg0 * sigmoidf_(hg0) * hv0; o[1][j] = hg1 * sigmoidf_(hg1) * hv1; o[2][j] = hg2 * sigmoidf_(hg2) * hv2; o[3][j] = hg3 * sigmoidf_(hg3) * hv3; }
; #pragma unroll
;                 for (int m = 0; m < 4; ++m) { u32x2 w; w.x = cvt_pk_bf16(o[m][0], o[m][1]); w.y = cvt_pk_bf16(o[m][2], o[m][3]);
;                     *(u32x2*)(Aout + (size_t)(row0 + ai * 128 + m) * FH + hc0 + 4 * n) = w; } } }
	v_pk_fma_f32 v[248:249], v[166:167], v[196:197], v[248:249]
	v_pk_mul_f32 v[202:203], v[206:207], v[202:203]
	v_pk_fma_f32 v[204:205], v[162:163], v[204:205], v[248:249]
	v_lshl_add_u32 v246, s42, 8, v236
	v_pk_mul_f32 v[202:203], v[204:205], v[202:203]
	v_lshlrev_b64 v[204:205], 1, v[232:233]
	v_pk_fma_f32 v[232:233], v[132:133], v[184:185], v[188:189]
	v_mov_b64_e32 v[206:207], s[60:61]
	v_pk_fma_f32 v[232:233], v[152:153], v[180:181], v[232:233]
	v_cvt_pk_bf16_f32 v209, v202, v203
	v_pk_fma_f32 v[198:199], v[176:177], v[198:199], v[232:233]
	v_mad_i64_i32 v[202:203], s[42:43], v246, s82, v[206:207]
	v_mul_f32_e32 v193, 0xbfb8aa3b, v198
	v_exp_f32_e32 v193, v193
	v_mul_f32_e32 v232, 0xbfb8aa3b, v199
	v_exp_f32_e32 v232, v232
	v_lshl_add_u64 v[202:203], v[202:203], 0, v[204:205]
	v_add_f32_e32 v193, 1.0, v193
	global_store_dwordx2 v[202:203], v[208:209], off
	v_rcp_f32_e32 v208, v193
	v_add_f32_e32 v193, 1.0, v232
	v_rcp_f32_e32 v209, v193
	v_pk_fma_f32 v[232:233], v[144:145], v[168:169], v[172:173]
	v_pk_fma_f32 v[140:141], v[140:141], v[184:185], v[188:189]
	v_pk_fma_f32 v[232:233], v[156:157], v[164:165], v[232:233]
	v_pk_mul_f32 v[198:199], v[198:199], v[208:209]
	v_pk_fma_f32 v[194:195], v[160:161], v[194:195], v[232:233]
	v_pk_fma_f32 v[208:209], v[146:147], v[170:171], v[174:175]
	v_pk_mul_f32 v[194:195], v[194:195], v[198:199]
	v_pk_fma_f32 v[198:199], v[134:135], v[186:187], v[190:191]
	v_pk_fma_f32 v[208:209], v[158:159], v[166:167], v[208:209]
	v_pk_fma_f32 v[198:199], v[154:155], v[182:183], v[198:199]
	v_pk_fma_f32 v[196:197], v[162:163], v[196:197], v[208:209]
	v_pk_fma_f32 v[198:199], v[178:179], v[200:201], v[198:199]
	v_cvt_pk_bf16_f32 v194, v194, v195
	v_mul_f32_e32 v193, 0xbfb8aa3b, v198
	v_exp_f32_e32 v193, v193
	v_mul_f32_e32 v200, 0xbfb8aa3b, v199
	v_exp_f32_e32 v201, v200
	v_pk_fma_f32 v[148:149], v[148:149], v[168:169], v[172:173]
	v_add_f32_e32 v193, 1.0, v193
	v_rcp_f32_e32 v200, v193
	v_add_f32_e32 v193, 1.0, v201
	v_rcp_f32_e32 v201, v193
	v_or_b32_e32 v193, 1, v246
	v_pk_mul_f32 v[198:199], v[198:199], v[200:201]
	s_nop 0
	v_pk_mul_f32 v[196:197], v[196:197], v[198:199]
	v_pk_fma_f32 v[198:199], v[128:129], v[184:185], v[188:189]
	v_cvt_pk_bf16_f32 v195, v196, v197
	v_pk_fma_f32 v[198:199], v[132:133], v[180:181], v[198:199]
	v_mad_i64_i32 v[196:197], s[42:43], v193, s82, v[206:207]
	v_pk_fma_f32 v[152:153], v[152:153], v[176:177], v[198:199]
	v_lshl_add_u64 v[196:197], v[196:197], 0, v[204:205]
	v_mul_f32_e32 v193, 0xbfb8aa3b, v152
	v_exp_f32_e32 v193, v193
	v_mul_f32_e32 v198, 0xbfb8aa3b, v153
	v_exp_f32_e32 v198, v198
	global_store_dwordx2 v[196:197], v[194:195], off
	v_add_f32_e32 v193, 1.0, v193
	v_rcp_f32_e32 v194, v193
	v_add_f32_e32 v193, 1.0, v198
	v_rcp_f32_e32 v195, v193
	v_pk_fma_f32 v[198:199], v[136:137], v[168:169], v[172:173]
	v_pk_fma_f32 v[128:129], v[128:129], v[180:181], v[140:141]
	v_pk_fma_f32 v[198:199], v[144:145], v[164:165], v[198:199]
	v_pk_fma_f32 v[128:129], v[132:133], v[176:177], v[128:129]
	v_pk_fma_f32 v[156:157], v[156:157], v[160:161], v[198:199]
	v_pk_mul_f32 v[152:153], v[152:153], v[194:195]
	v_mul_f32_e32 v132, 0xbfb8aa3b, v128
	v_pk_mul_f32 v[152:153], v[156:157], v[152:153]
	v_pk_fma_f32 v[156:157], v[130:131], v[186:187], v[190:191]
	v_exp_f32_e32 v140, v132
	v_pk_fma_f32 v[132:133], v[142:143], v[186:187], v[190:191]
	v_pk_fma_f32 v[156:157], v[134:135], v[182:183], v[156:157]
	v_pk_fma_f32 v[130:131], v[130:131], v[182:183], v[132:133]
	v_pk_fma_f32 v[154:155], v[154:155], v[178:179], v[156:157]
	v_pk_fma_f32 v[130:131], v[134:135], v[178:179], v[130:131]
	v_mul_f32_e32 v156, 0xbfb8aa3b, v154
	v_mul_f32_e32 v141, 0xbfb8aa3b, v129
	v_mul_f32_e32 v132, 0xbfb8aa3b, v130
	v_mul_f32_e32 v133, 0xbfb8aa3b, v131
	v_exp_f32_e32 v157, v156
	v_mul_f32_e32 v156, 0xbfb8aa3b, v155
	v_exp_f32_e32 v141, v141
	v_exp_f32_e32 v132, v132
	v_exp_f32_e32 v133, v133
	v_exp_f32_e32 v193, v156
	v_add_f32_e32 v140, 1.0, v140
	v_add_f32_e32 v141, 1.0, v141
	v_add_f32_e32 v132, 1.0, v132
	v_add_f32_e32 v133, 1.0, v133
	v_cvt_pk_bf16_f32 v156, v152, v153
	v_add_f32_e32 v152, 1.0, v157
	v_add_f32_e32 v153, 1.0, v193
	v_rcp_f32_e32 v140, v140
	v_rcp_f32_e32 v141, v141
	v_rcp_f32_e32 v132, v132
	v_rcp_f32_e32 v133, v133
	v_rcp_f32_e32 v152, v152
	v_rcp_f32_e32 v153, v153
	v_pk_fma_f32 v[142:143], v[150:151], v[170:171], v[174:175]
	v_pk_fma_f32 v[194:195], v[138:139], v[170:171], v[174:175]
	v_pk_fma_f32 v[136:137], v[136:137], v[164:165], v[148:149]
	v_pk_fma_f32 v[134:135], v[138:139], v[166:167], v[142:143]
	v_pk_fma_f32 v[194:195], v[146:147], v[166:167], v[194:195]
	v_pk_fma_f32 v[136:137], v[144:145], v[160:161], v[136:137]
	v_pk_mul_f32 v[128:129], v[128:129], v[140:141]
	v_pk_fma_f32 v[134:135], v[146:147], v[162:163], v[134:135]
	v_pk_mul_f32 v[130:131], v[130:131], v[132:133]
	v_pk_fma_f32 v[158:159], v[158:159], v[162:163], v[194:195]
	v_pk_mul_f32 v[152:153], v[154:155], v[152:153]
	v_pk_mul_f32 v[128:129], v[136:137], v[128:129]
	v_pk_mul_f32 v[130:131], v[134:135], v[130:131]
	v_pk_mul_f32 v[152:153], v[158:159], v[152:153]
	v_cvt_pk_bf16_f32 v128, v128, v129
	v_cvt_pk_bf16_f32 v129, v130, v131
	v_or_b32_e32 v130, 3, v246
	v_cvt_pk_bf16_f32 v157, v152, v153
	v_or_b32_e32 v152, 2, v246
	v_mad_i64_i32 v[130:131], s[42:43], v130, s82, v[206:207]
	v_mad_i64_i32 v[152:153], s[42:43], v152, s82, v[206:207]
	v_lshl_add_u64 v[140:141], v[130:131], 0, v[204:205]
	v_lshl_add_u64 v[152:153], v[152:153], 0, v[204:205]
	global_store_dwordx2 v[140:141], v[128:129], off
	v_mov_b32_e32 v193, 0
	v_mov_b32_e32 v194, 0
	v_mov_b32_e32 v195, 0
	v_mov_b32_e32 v136, 0
	v_mov_b32_e32 v137, 0
	v_mov_b32_e32 v138, 0
	v_mov_b32_e32 v139, 0
	v_mov_b32_e32 v128, 0
	v_mov_b32_e32 v129, 0
	v_mov_b32_e32 v130, 0
	v_mov_b32_e32 v131, 0
	v_mov_b32_e32 v132, 0
	v_mov_b32_e32 v133, 0
	v_mov_b32_e32 v134, 0
	v_mov_b32_e32 v135, 0
	global_store_dwordx2 v[152:153], v[156:157], off
	s_and_saveexec_b64 s[42:43], s[30:31]
	s_cbranch_execz .LBB0_1370
	ds_read_b128 v[132:135], v237 offset:2048
	ds_read_b128 v[136:139], v237 offset:2560
	ds_read_b128 v[128:131], v237 offset:3072
	ds_read_b128 v[192:195], v237 offset:3584

;     __device__ __forceinline__ void operator()(AccRef acc, const Unit& u, int wr, int wc, int fr, int fq) const {
;     ...
;         float* rawu = raw + (size_t)(u.pm * 22 + u.pn) * 1024;
;         if (wr == 0 && fr == 0) {
; #pragma unroll
;             for (int bj = 0; bj < 2; ++bj)
; #pragma unroll
;                 for (int n = 0; n < 2; ++n) { *(f32x4*)(rawu + 0 * 256 + bj * 128 + clb + 4 * n) = acc[0][bj][0][n]; *(f32x4*)(rawu + 1 * 256 + bj * 128 + clb + 4 * n) = acc[0][bj][1][n]; }
;         }
;         if (wr == 1 && fr == 15) {
; #pragma unroll
;             for (int bj = 0; bj < 2; ++bj)
; #pragma unroll
;                 for (int n = 0; n < 2; ++n) { *(f32x4*)(rawu + 2 * 256 + bj * 128 + clb + 4 * n) = acc[1][bj][2][n]; *(f32x4*)(rawu + 3 * 256 + bj * 128 + clb + 4 * n) = acc[1][bj][3][n]; }
;         }
;         asm volatile("s_waitcnt lgkmcnt(0)" ::: "memory"); __builtin_amdgcn_s_barrier(); __builtin_amdgcn_s_barrier(); asm volatile("" ::: "memory");
;         const int hc0 = 128 * u.pn + clb, row0 = u.pm * 256 + wr * 64 + 4 * fr;
; #pragma unroll
;         for (int n = 0; n < 2; ++n) {
;             const f32x4 w0v = cwv[n][0], w1v = cwv[n][1], w2v = cwv[n][2], bvv = cwv[n][3], w0g = cwv[n][4], w1g = cwv[n][5], w2g = cwv[n][6], bvg = cwv[n][7];
; #pragma unroll
;             for (int ai = 0; ai < 2; ++ai) {
;                 if (n == 0 && ai == 0) {
;                     asm volatile("" ::: "memory");
;                     const float* cv = cw + hc0 + 4; const float* cg = cv + FH; const float* bp = cb + hc0 + 4;
;                     cwv[1][0] = *(const f32x4*)(cv); cwv[1][1] = *(const f32x4*)(cv + F2); cwv[1][2] = *(const f32x4*)(cv + 2 * F2); cwv[1][3] = *(const f32x4*)(bp);
;                     cwv[1][4] = *(const f32x4*)(cg); cwv[1][5] = *(const f32x4*)(cg + F2); cwv[1][6] = *(const f32x4*)(cg + 2 * F2); cwv[1][7] = *(const f32x4*)(bp + FH);
;                     asm volatile("" ::: "memory"); }
;                 f32x4 h2v = (f32x4){0.f, 0.f, 0.f, 0.f}, h3v = h2v, h2g = h2v, h3g = h2v;
;                 const int pb = ai * 2 + wr - 1;
;                 if (pb >= 0 && fr == 0) { const LAS float* xp = xch + (pb * 2) * 256 + clb + 4 * n;
;                     h2v = *(const LAS f32x4*)(xp); h3v = *(const LAS f32x4*)(xp + 256); h2g = *(const LAS f32x4*)(xp + 128); h3g = *(const LAS f32x4*)(xp + 256 + 128); }
.LBB0_1943:
	s_or_b64 exec, exec, s[38:39]
	s_mul_i32 s25, s34, 22
	s_add_i32 s38, s25, s35
	s_ashr_i32 s39, s38, 31
	s_lshl_b64 s[38:39], s[38:39], 12
	s_add_u32 s38, s64, s38
	s_addc_u32 s39, s65, s39
	v_lshlrev_b32_e32 v96, 2, v218
	v_or_b32_e32 v232, s36, v218
	v_ashrrev_i32_e32 v233, 31, v232
	v_lshlrev_b64 v[96:97], 2, v[232:233]
	v_lshl_add_u64 v[120:121], s[12:13], 0, v[96:97]
	v_add_co_u32_e32 v100, vcc, 0x5000, v120
	s_waitcnt lgkmcnt(0)
	s_barrier
	s_nop 0
	v_addc_co_u32_e32 v101, vcc, 0, v121, vcc
	v_add_co_u32_e32 v104, vcc, 0xb000, v120
	s_barrier
	s_nop 0
	v_addc_co_u32_e32 v105, vcc, 0, v121, vcc
	v_add_co_u32_e32 v112, vcc, s49, v120
	v_lshl_add_u64 v[124:125], s[14:15], 0, v[96:97]
	s_nop 0
	v_addc_co_u32_e32 v113, vcc, 0, v121, vcc
	v_add_co_u32_e32 v116, vcc, 0x8000, v120
	global_load_dwordx4 v[96:99], v[120:121], off offset:16
	s_nop 0
	v_addc_co_u32_e32 v117, vcc, 0, v121, vcc
	v_add_co_u32_e32 v120, vcc, 0xd000, v120
	global_load_dwordx4 v[100:103], v[100:101], off offset:2064
	s_nop 0
	global_load_dwordx4 v[104:107], v[104:105], off offset:16
	s_nop 0
	global_load_dwordx4 v[108:111], v[124:125], off offset:16
	v_addc_co_u32_e32 v121, vcc, 0, v121, vcc
	v_add_co_u32_e32 v124, vcc, 0x2000, v124
	global_load_dwordx4 v[112:115], v[112:113], off offset:3088
	s_nop 0
	global_load_dwordx4 v[116:119], v[116:117], off offset:1040
	v_addc_co_u32_e32 v125, vcc, 0, v125, vcc
	global_load_dwordx4 v[120:123], v[120:121], off offset:3088
	v_mov_b32_e32 v192, 0
	global_load_dwordx4 v[124:127], v[124:125], off offset:3088
	v_mov_b32_e32 v198, 0
	v_mov_b32_e32 v199, 0
	v_mov_b32_e32 v200, 0
	v_mov_b32_e32 v201, 0
	v_mov_b32_e32 v206, 0
	v_mov_b32_e32 v207, 0
	v_mov_b32_e32 v208, 0
	v_mov_b32_e32 v209, 0
	v_mov_b32_e32 v194, 0
	v_mov_b32_e32 v195, 0
	v_mov_b32_e32 v196, 0
	v_mov_b32_e32 v197, 0
	v_mov_b32_e32 v202, 0
	v_mov_b32_e32 v203, 0
	v_mov_b32_e32 v204, 0
	v_mov_b32_e32 v205, 0
	s_and_saveexec_b64 s[36:37], s[20:21]
	s_cbranch_execz .LBB0_1949
	ds_read_b128 v[202:205], v237
	ds_read_b128 v[206:209], v237 offset:512
	ds_read_b128 v[194:197], v237 offset:1024
	ds_read_b128 v[198:201], v237 offset:1536
.LBB0_1949:
	s_or_b64 exec, exec, s[36:37]
	s_waitcnt lgkmcnt(0)
	v_mov_b32_dpp v198, v140 row_shr:1 row_mask:0xf bank_mask:0xf
	v_mov_b32_dpp v199, v141 row_shr:1 row_mask:0xf bank_mask:0xf
	s_waitcnt vmcnt(8)
	v_lshlrev_b32_e32 v253, 2, v218
	s_and_saveexec_b64 s[40:41], s[8:9]
	s_cbranch_execz .LBB0_1945
	global_store_dwordx4 v253, v[156:159], s[38:39]
	global_store_dwordx4 v253, v[144:147], s[38:39] offset:1024
	global_store_dwordx4 v253, v[60:63], s[38:39] offset:16
	global_store_dwordx4 v253, v[48:51], s[38:39] offset:1040
	global_store_dwordx4 v253, v[152:155], s[38:39] offset:512
	global_store_dwordx4 v253, v[132:135], s[38:39] offset:1536
	global_store_dwordx4 v253, v[56:59], s[38:39] offset:528
	global_store_dwordx4 v253, v[36:39], s[38:39] offset:1552
.LBB0_1945:
	s_or_b64 exec, exec, s[40:41]
	s_and_saveexec_b64 s[40:41], s[18:19]
	s_cbranch_execz .LBB0_1947
	global_store_dwordx4 v253, v[76:79], s[38:39] offset:2048
	global_store_dwordx4 v253, v[84:87], s[38:39] offset:3072
	global_store_dwordx4 v253, v[12:15], s[38:39] offset:2064
	global_store_dwordx4 v253, v[20:23], s[38:39] offset:3088
	global_store_dwordx4 v253, v[64:67], s[38:39] offset:2560
	global_store_dwordx4 v253, v[72:75], s[38:39] offset:3584
	global_store_dwordx4 v253, v[0:3], s[38:39] offset:2576
	global_store_dwordx4 v253, v[8:11], s[38:39] offset:3600
.LBB0_1947:
	s_or_b64 exec, exec, s[40:41]
	v_pk_fma_f32 v[246:247], v[152:153], v[184:185], v[188:189]
	v_mov_b32_dpp v206, v128 row_shr:1 row_mask:0xf bank_mask:0xf
	v_mov_b32_dpp v207, v129 row_shr:1 row_mask:0xf bank_mask:0xf
	v_pk_fma_f32 v[246:247], v[180:181], v[198:199], v[246:247]
	v_mov_b32_dpp v194, v148 row_shr:1 row_mask:0xf bank_mask:0xf
	v_pk_fma_f32 v[206:207], v[176:177], v[206:207], v[246:247]
	v_mov_b32_dpp v195, v149 row_shr:1 row_mask:0xf bank_mask:0xf
	v_mul_f32_e32 v193, 0xbfb8aa3b, v206
	v_exp_f32_e32 v193, v193
	v_mul_f32_e32 v246, 0xbfb8aa3b, v207
	v_exp_f32_e32 v247, v246
	v_pk_fma_f32 v[248:249], v[156:157], v[168:169], v[172:173]
	v_add_f32_e32 v193, 1.0, v193
	v_rcp_f32_e32 v246, v193
	v_add_f32_e32 v193, 1.0, v247
	v_rcp_f32_e32 v247, v193
	v_mov_b32_dpp v202, v136 row_shr:1 row_mask:0xf bank_mask:0xf
	v_mov_b32_dpp v203, v137 row_shr:1 row_mask:0xf bank_mask:0xf
	v_pk_fma_f32 v[248:249], v[164:165], v[194:195], v[248:249]
	v_pk_mul_f32 v[206:207], v[206:207], v[246:247]
	v_pk_fma_f32 v[202:203], v[160:161], v[202:203], v[248:249]
	v_mov_b32_dpp v200, v142 row_shr:1 row_mask:0xf bank_mask:0xf
	v_mov_b32_dpp v201, v143 row_shr:1 row_mask:0xf bank_mask:0xf
	v_pk_mul_f32 v[202:203], v[202:203], v[206:207]
	v_pk_fma_f32 v[206:207], v[154:155], v[186:187], v[190:191]
	v_mov_b32_dpp v208, v130 row_shr:1 row_mask:0xf bank_mask:0xf
	v_mov_b32_dpp v209, v131 row_shr:1 row_mask:0xf bank_mask:0xf
	v_pk_fma_f32 v[206:207], v[182:183], v[200:201], v[206:207]
	v_mov_b32_dpp v196, v150 row_shr:1 row_mask:0xf bank_mask:0xf
	v_pk_fma_f32 v[206:207], v[178:179], v[208:209], v[206:207]
	v_mov_b32_dpp v197, v151 row_shr:1 row_mask:0xf bank_mask:0xf
	v_mul_f32_e32 v193, 0xbfb8aa3b, v206
	v_exp_f32_e32 v193, v193
	v_mul_f32_e32 v208, 0xbfb8aa3b, v207
	v_exp_f32_e32 v209, v208
	v_cvt_pk_bf16_f32 v208, v202, v203
	v_add_f32_e32 v193, 1.0, v193
	v_rcp_f32_e32 v202, v193
	v_add_f32_e32 v193, 1.0, v209
	v_rcp_f32_e32 v203, v193
	v_pk_fma_f32 v[246:247], v[158:159], v[170:171], v[174:175]
	v_mov_b32_dpp v204, v138 row_shr:1 row_mask:0xf bank_mask:0xf
	v_mov_b32_dpp v205, v139 row_shr:1 row_mask:0xf bank_mask:0xf
; #define LAS __attribute__((address_space(3)))
; __device__ __forceinline__ float sigmoidf_(float x) { return __builtin_amdgcn_rcpf(1.0f + __expf(-x)); }
;     __device__ __forceinline__ void operator()(AccRef acc, const Unit& u, int wr, int wc, int fr, int fq) const {
;     ...
;                 f32x4 h2v = (f32x4){0.f, 0.f, 0.f, 0.f}, h3v = h2v, h2g = h2v, h3g = h2v;
;                 const int pb = ai * 2 + wr - 1;
;                 if (pb >= 0 && fr == 0) { const LAS float* xp = xch + (pb * 2) * 256 + clb + 4 * n;
;                     h2v = *(const LAS f32x4*)(xp); h3v = *(const LAS f32x4*)(xp + 256); h2g = *(const LAS f32x4*)(xp + 128); h3g = *(const LAS f32x4*)(xp + 256 + 128); }
;                 float o[4][4];
; #pragma unroll
;                 for (int j = 0; j < 4; ++j) {
;                     const float v0 = acc[ai][0][0][n][j], v1 = acc[ai][0][1][n][j], v2 = acc[ai][0][2][n][j], v3 = acc[ai][0][3][n][j];
;                     const float g0 = acc[ai][1][0][n][j], g1 = acc[ai][1][1][n][j], g2 = acc[ai][1][2][n][j], g3 = acc[ai][1][3][n][j];
;                     const float pv3 = dpp_upd<0x111>(h3v[j], v3), pv2 = dpp_upd<0x111>(h2v[j], v2), pg3 = dpp_upd<0x111>(h3g[j], g3), pg2 = dpp_upd<0x111>(h2g[j], g2);
;                     const float hv0 = bvv[j] + w2v[j] * v0 + w1v[j] * pv3 + w0v[j] * pv2, hv1 = bvv[j] + w2v[j] * v1 + w1v[j] * v0 + w0v[j] * pv3;
;                     const float hv2 = bvv[j] + w2v[j] * v2 + w1v[j] * v1 + w0v[j] * v0, hv3 = bvv[j] + w2v[j] * v3 + w1v[j] * v2 + w0v[j] * v1;
;                     const float hg0 = bvg[j] + w2g[j] * g0 + w1g[j] * pg3 + w0g[j] * pg2, hg1 = bvg[j] + w2g[j] * g1 + w1g[j] * g0 + w0g[j] * pg3;
;                     const float hg2 = bvg[j] + w2g[j] * g2 + w1g[j] * g1 + w0g[j] * g0, hg3 = bvg[j] + w2g[j] * g3 + w1g[j] * g2 + w0g[j] * g1;
;                     o[0][j] = hg0 * sigmoidf_(hg0) * hv0; o[1][j] = hg1 * sigmoidf_(hg1) * hv1; o[2][j] = hg2 * sigmoidf_(hg2) * hv2; o[3][j] = hg3 * sigmoidf_(hg3) * hv3; }
; #pragma unroll
;                 for (int m = 0; m < 4; ++m) { u32x2 w; w.x = cvt_pk_bf16(o[m][0], o[m][1]); w.y = cvt_pk_bf16(o[m][2], o[m][3]);
;                     *(u32x2*)(Aout + (size_t)(row0 + ai * 128 + m) * FH + hc0 + 4 * n) = w; } } }
	v_pk_fma_f32 v[246:247], v[166:167], v[196:197], v[246:247]
	v_pk_mul_f32 v[202:203], v[206:207], v[202:203]
	v_pk_fma_f32 v[204:205], v[162:163], v[204:205], v[246:247]
	v_lshl_add_u32 v245, s34, 8, v235
	v_pk_mul_f32 v[202:203], v[204:205], v[202:203]
	v_lshlrev_b64 v[204:205], 1, v[232:233]
	v_pk_fma_f32 v[232:233], v[132:133], v[184:185], v[188:189]
	v_mov_b64_e32 v[206:207], s[60:61]
	v_pk_fma_f32 v[232:233], v[152:153], v[180:181], v[232:233]
	v_cvt_pk_bf16_f32 v209, v202, v203
	v_pk_fma_f32 v[198:199], v[176:177], v[198:199], v[232:233]
	v_mad_i64_i32 v[202:203], s[34:35], v245, s63, v[206:207]
	v_mul_f32_e32 v193, 0xbfb8aa3b, v198
	v_exp_f32_e32 v193, v193
	v_mul_f32_e32 v232, 0xbfb8aa3b, v199
	v_exp_f32_e32 v232, v232
	v_lshl_add_u64 v[202:203], v[202:203], 0, v[204:205]
	v_add_f32_e32 v193, 1.0, v193
	global_store_dwordx2 v[202:203], v[208:209], off
	v_rcp_f32_e32 v208, v193
	v_add_f32_e32 v193, 1.0, v232
	v_rcp_f32_e32 v209, v193
	v_pk_fma_f32 v[232:233], v[144:145], v[168:169], v[172:173]
	v_pk_fma_f32 v[140:141], v[140:141], v[184:185], v[188:189]
	v_pk_fma_f32 v[232:233], v[156:157], v[164:165], v[232:233]
	v_pk_mul_f32 v[198:199], v[198:199], v[208:209]
	v_pk_fma_f32 v[194:195], v[160:161], v[194:195], v[232:233]
	v_pk_fma_f32 v[208:209], v[146:147], v[170:171], v[174:175]
	v_pk_mul_f32 v[194:195], v[194:195], v[198:199]
	v_pk_fma_f32 v[198:199], v[134:135], v[186:187], v[190:191]
	v_pk_fma_f32 v[208:209], v[158:159], v[166:167], v[208:209]
	v_pk_fma_f32 v[198:199], v[154:155], v[182:183], v[198:199]
	v_pk_fma_f32 v[196:197], v[162:163], v[196:197], v[208:209]
	v_pk_fma_f32 v[198:199], v[178:179], v[200:201], v[198:199]
	v_cvt_pk_bf16_f32 v194, v194, v195
	v_mul_f32_e32 v193, 0xbfb8aa3b, v198
	v_exp_f32_e32 v193, v193
	v_mul_f32_e32 v200, 0xbfb8aa3b, v199
	v_exp_f32_e32 v201, v200
	v_pk_fma_f32 v[148:149], v[148:149], v[168:169], v[172:173]
	v_add_f32_e32 v193, 1.0, v193
	v_rcp_f32_e32 v200, v193
	v_add_f32_e32 v193, 1.0, v201
	v_rcp_f32_e32 v201, v193
	v_or_b32_e32 v193, 1, v245
	v_pk_mul_f32 v[198:199], v[198:199], v[200:201]
	s_nop 0
	v_pk_mul_f32 v[196:197], v[196:197], v[198:199]
	v_pk_fma_f32 v[198:199], v[128:129], v[184:185], v[188:189]
	v_cvt_pk_bf16_f32 v195, v196, v197
	v_pk_fma_f32 v[198:199], v[132:133], v[180:181], v[198:199]
	v_mad_i64_i32 v[196:197], s[34:35], v193, s63, v[206:207]
	v_pk_fma_f32 v[152:153], v[152:153], v[176:177], v[198:199]
	v_lshl_add_u64 v[196:197], v[196:197], 0, v[204:205]
	v_mul_f32_e32 v193, 0xbfb8aa3b, v152
	v_exp_f32_e32 v193, v193
	v_mul_f32_e32 v198, 0xbfb8aa3b, v153
	v_exp_f32_e32 v198, v198
	global_store_dwordx2 v[196:197], v[194:195], off
	v_add_f32_e32 v193, 1.0, v193
	v_rcp_f32_e32 v194, v193
	v_add_f32_e32 v193, 1.0, v198
	v_rcp_f32_e32 v195, v193
	v_pk_fma_f32 v[198:199], v[136:137], v[168:169], v[172:173]
	v_pk_fma_f32 v[128:129], v[128:129], v[180:181], v[140:141]
	v_pk_fma_f32 v[198:199], v[144:145], v[164:165], v[198:199]
	v_pk_fma_f32 v[128:129], v[132:133], v[176:177], v[128:129]
	v_pk_fma_f32 v[156:157], v[156:157], v[160:161], v[198:199]
	v_pk_mul_f32 v[152:153], v[152:153], v[194:195]
	v_mul_f32_e32 v132, 0xbfb8aa3b, v128
	v_pk_mul_f32 v[152:153], v[156:157], v[152:153]
	v_pk_fma_f32 v[156:157], v[130:131], v[186:187], v[190:191]
	v_exp_f32_e32 v140, v132
	v_pk_fma_f32 v[132:133], v[142:143], v[186:187], v[190:191]
	v_pk_fma_f32 v[156:157], v[134:135], v[182:183], v[156:157]
	v_pk_fma_f32 v[130:131], v[130:131], v[182:183], v[132:133]
	v_pk_fma_f32 v[154:155], v[154:155], v[178:179], v[156:157]
	v_pk_fma_f32 v[130:131], v[134:135], v[178:179], v[130:131]
	v_mul_f32_e32 v156, 0xbfb8aa3b, v154
	v_mul_f32_e32 v141, 0xbfb8aa3b, v129
	v_mul_f32_e32 v132, 0xbfb8aa3b, v130
	v_mul_f32_e32 v133, 0xbfb8aa3b, v131
	v_exp_f32_e32 v157, v156
	v_mul_f32_e32 v156, 0xbfb8aa3b, v155
	v_exp_f32_e32 v141, v141
	v_exp_f32_e32 v132, v132
	v_exp_f32_e32 v133, v133
	v_exp_f32_e32 v193, v156
	v_add_f32_e32 v140, 1.0, v140
	v_add_f32_e32 v141, 1.0, v141
	v_add_f32_e32 v132, 1.0, v132
	v_add_f32_e32 v133, 1.0, v133
	v_cvt_pk_bf16_f32 v156, v152, v153
	v_add_f32_e32 v152, 1.0, v157
	v_add_f32_e32 v153, 1.0, v193
	v_rcp_f32_e32 v140, v140
	v_rcp_f32_e32 v141, v141
	v_rcp_f32_e32 v132, v132
	v_rcp_f32_e32 v133, v133
	v_rcp_f32_e32 v152, v152
	v_rcp_f32_e32 v153, v153
	v_pk_fma_f32 v[142:143], v[150:151], v[170:171], v[174:175]
	v_pk_fma_f32 v[194:195], v[138:139], v[170:171], v[174:175]
	v_pk_fma_f32 v[136:137], v[136:137], v[164:165], v[148:149]
	v_pk_fma_f32 v[134:135], v[138:139], v[166:167], v[142:143]
	v_pk_fma_f32 v[194:195], v[146:147], v[166:167], v[194:195]
	v_pk_fma_f32 v[136:137], v[144:145], v[160:161], v[136:137]
	v_pk_mul_f32 v[128:129], v[128:129], v[140:141]
	v_pk_fma_f32 v[134:135], v[146:147], v[162:163], v[134:135]
	v_pk_mul_f32 v[130:131], v[130:131], v[132:133]
	v_pk_fma_f32 v[158:159], v[158:159], v[162:163], v[194:195]
	v_pk_mul_f32 v[152:153], v[154:155], v[152:153]
	v_pk_mul_f32 v[128:129], v[136:137], v[128:129]
	v_pk_mul_f32 v[130:131], v[134:135], v[130:131]
	v_pk_mul_f32 v[152:153], v[158:159], v[152:153]
	v_cvt_pk_bf16_f32 v128, v128, v129
	v_cvt_pk_bf16_f32 v129, v130, v131
	v_or_b32_e32 v130, 3, v245
	v_cvt_pk_bf16_f32 v157, v152, v153
	v_or_b32_e32 v152, 2, v245
	v_mad_i64_i32 v[130:131], s[34:35], v130, s63, v[206:207]
	v_mad_i64_i32 v[152:153], s[34:35], v152, s63, v[206:207]
	v_lshl_add_u64 v[140:141], v[130:131], 0, v[204:205]
	v_lshl_add_u64 v[152:153], v[152:153], 0, v[204:205]
	global_store_dwordx2 v[140:141], v[128:129], off
	v_mov_b32_e32 v193, 0
	v_mov_b32_e32 v194, 0
	v_mov_b32_e32 v195, 0
	v_mov_b32_e32 v136, 0
	v_mov_b32_e32 v137, 0
	v_mov_b32_e32 v138, 0
	v_mov_b32_e32 v139, 0
	v_mov_b32_e32 v128, 0
	v_mov_b32_e32 v129, 0
	v_mov_b32_e32 v130, 0
	v_mov_b32_e32 v131, 0
	v_mov_b32_e32 v132, 0
	v_mov_b32_e32 v133, 0
	v_mov_b32_e32 v134, 0
	v_mov_b32_e32 v135, 0
	global_store_dwordx2 v[152:153], v[156:157], off
	s_and_saveexec_b64 s[34:35], s[22:23]
	s_cbranch_execz .LBB0_1951
	ds_read_b128 v[132:135], v236 offset:2048
	ds_read_b128 v[136:139], v236 offset:2560
	ds_read_b128 v[128:131], v236 offset:3072
	ds_read_b128 v[192:195], v236 offset:3584
